# P4 weight-prep transposes: 8 serial load/wait/LDS-write steps per item pipelined over three register buffers with counted vmcnt (on top of P8 epilogue counted waits)
# baseline (speedup 1.0000x reference)
.LBB0_153:
	s_and_b64 vcc, exec, s[18:19]
	s_cbranch_vccz .LBB0_155
	s_add_i32 s18, s44, 0xffffe880
	s_lshr_b32 s92, s18, 2
	v_readlane_b32 s52, v254, 42
	s_cmp_lt_u32 s18, 4
	v_readlane_b32 s56, v254, 46
	v_readlane_b32 s62, v254, 52
	v_readlane_b32 s57, v254, 47
	v_readlane_b32 s63, v254, 53
	s_cselect_b32 s19, s56, s62
	s_cselect_b32 s18, s57, s63
	s_add_u32 s19, s19, s16
	s_addc_u32 s20, s18, s17
	s_lshl_b32 s21, s44, 5
	s_and_b32 s18, s21, 32
	s_lshl_b32 s22, s18, 2
	s_add_u32 s22, s19, s22
	s_addc_u32 s23, s20, 0
	s_and_b32 s19, s21, 64
	s_waitcnt lgkmcnt(0)
	v_add_u32_e32 v0, s19, v37
	v_lshlrev_b32_e32 v136, 2, v8
	v_ashrrev_i32_e32 v1, 31, v0
	v_lshl_add_u64 v[4:5], s[22:23], 0, v[136:137]
	v_lshlrev_b64 v[0:1], 8, v[0:1]
	v_lshl_add_u64 v[0:1], v[4:5], 0, v[0:1]
	global_load_dwordx4 v[0:3], v[0:1], off
	v_add_u32_e32 v236, s19, v40
	v_ashrrev_i32_e32 v237, 31, v236
	v_lshlrev_b64 v[236:237], 8, v[236:237]
	v_lshl_add_u64 v[236:237], v[4:5], 0, v[236:237]
	global_load_dwordx4 v[228:231], v[236:237], off
	v_add_u32_e32 v236, s19, v41
	v_ashrrev_i32_e32 v237, 31, v236
	v_lshlrev_b64 v[236:237], 8, v[236:237]
	v_lshl_add_u64 v[236:237], v[4:5], 0, v[236:237]
	global_load_dwordx4 v[232:235], v[236:237], off
	v_add_u32_e32 v6, v38, v39
	v_add_u32_e32 v7, 0x420, v6
	s_lshl_b64 s[20:21], s[92:93], 14
	s_add_u32 s20, s39, s20
	s_addc_u32 s21, s40, s21
	v_lshlrev_b32_e32 v136, 1, v10
	s_movk_i32 s6, 0x300
	v_readlane_b32 s53, v254, 43
	v_readlane_b32 s54, v254, 44
	v_readlane_b32 s55, v254, 45
	v_readlane_b32 s58, v254, 48
	v_readlane_b32 s59, v254, 49
	v_readlane_b32 s60, v254, 50
	v_readlane_b32 s61, v254, 51
	v_readlane_b32 s64, v254, 54
	v_readlane_b32 s65, v254, 55
	v_readlane_b32 s66, v254, 56
	v_readlane_b32 s67, v254, 57
	s_waitcnt vmcnt(2)
	ds_write2_b32 v6, v0, v1 offset1:1
	ds_write2_b32 v6, v2, v3 offset0:2 offset1:3
	v_add_u32_e32 v0, s19, v42
	v_ashrrev_i32_e32 v1, 31, v0
	v_lshlrev_b64 v[0:1], 8, v[0:1]
	v_lshl_add_u64 v[0:1], v[4:5], 0, v[0:1]
	global_load_dwordx4 v[0:3], v[0:1], off
	s_waitcnt vmcnt(2)
	ds_write2_b32 v7, v228, v229 offset1:1
	v_add_u32_e32 v236, 0x428, v6
	ds_write2_b32 v236, v230, v231 offset1:1
	v_add_u32_e32 v236, s19, v43
	v_ashrrev_i32_e32 v237, 31, v236
	v_lshlrev_b64 v[236:237], 8, v[236:237]
	v_lshl_add_u64 v[236:237], v[4:5], 0, v[236:237]
	global_load_dwordx4 v[228:231], v[236:237], off
	v_add_u32_e32 v7, 0x840, v6
	s_waitcnt vmcnt(2)
	ds_write2_b32 v7, v232, v233 offset1:1
	v_add_u32_e32 v236, 0x848, v6
	ds_write2_b32 v236, v234, v235 offset1:1
	v_add_u32_e32 v236, s19, v44
	v_ashrrev_i32_e32 v237, 31, v236
	v_lshlrev_b64 v[236:237], 8, v[236:237]
	v_lshl_add_u64 v[236:237], v[4:5], 0, v[236:237]
	global_load_dwordx4 v[232:235], v[236:237], off
	v_add_u32_e32 v7, 0xc60, v6
	s_waitcnt vmcnt(2)
	ds_write2_b32 v7, v0, v1 offset1:1
	v_add_u32_e32 v0, 0xc68, v6
	ds_write2_b32 v0, v2, v3 offset1:1
	v_add_u32_e32 v0, s19, v45
	v_ashrrev_i32_e32 v1, 31, v0
	v_lshlrev_b64 v[0:1], 8, v[0:1]
	v_lshl_add_u64 v[0:1], v[4:5], 0, v[0:1]
	global_load_dwordx4 v[0:3], v[0:1], off
	v_add_u32_e32 v7, 0x1080, v6
	s_waitcnt vmcnt(2)
	ds_write2_b32 v7, v228, v229 offset1:1
	v_add_u32_e32 v236, 0x1088, v6
	ds_write2_b32 v236, v230, v231 offset1:1
	v_add_u32_e32 v236, s19, v46
	v_ashrrev_i32_e32 v237, 31, v236
	v_lshlrev_b64 v[236:237], 8, v[236:237]
	v_lshl_add_u64 v[236:237], v[4:5], 0, v[236:237]
	global_load_dwordx4 v[228:231], v[236:237], off
	v_add_u32_e32 v7, 0x14a0, v6
	s_waitcnt vmcnt(2)
	ds_write2_b32 v7, v232, v233 offset1:1
	v_add_u32_e32 v236, 0x14a8, v6
	ds_write2_b32 v236, v234, v235 offset1:1
	v_add_u32_e32 v7, 0x18c0, v6
	s_waitcnt vmcnt(1)
	ds_write2_b32 v7, v0, v1 offset1:1
	v_add_u32_e32 v0, 0x18c8, v6
	ds_write2_b32 v0, v2, v3 offset1:1
	v_add_u32_e32 v4, 0x1ce0, v6
	s_lshl_b32 s19, s19, 1
	s_add_u32 s20, s20, s19
	s_addc_u32 s21, s21, 0
	s_waitcnt vmcnt(0)
	ds_write2_b32 v4, v228, v229 offset1:1
	v_add_u32_e32 v236, 0x1ce8, v6
	ds_write2_b32 v236, v230, v231 offset1:1
	s_waitcnt lgkmcnt(0)
	ds_read_b32 v2, v47
	ds_read_b32 v3, v47 offset:132
	v_lshl_add_u64 v[0:1], s[20:21], 0, v[136:137]
	s_waitcnt lgkmcnt(0)
	v_cvt_pk_bf16_f32 v2, v2, v3
	ds_read_b32 v3, v47 offset:264
	ds_read_b32 v4, v47 offset:396
	s_waitcnt lgkmcnt(0)
	v_cvt_pk_bf16_f32 v3, v3, v4
	ds_read_b32 v4, v47 offset:528
	ds_read_b32 v5, v47 offset:660
	s_waitcnt lgkmcnt(0)
	v_cvt_pk_bf16_f32 v4, v4, v5
	ds_read_b32 v5, v47 offset:792
	ds_read_b32 v6, v47 offset:924
	s_waitcnt lgkmcnt(0)
	v_cvt_pk_bf16_f32 v5, v5, v6
	v_add_u32_e32 v6, s18, v37
	v_ashrrev_i32_e32 v7, 31, v6
	v_lshlrev_b64 v[6:7], 8, v[6:7]
	v_lshl_add_u64 v[6:7], v[0:1], 0, v[6:7]
	global_store_dwordx4 v[6:7], v[2:5], off
	ds_read_b32 v2, v47 offset:32
	ds_read_b32 v3, v47 offset:164
	s_waitcnt lgkmcnt(0)
	v_cvt_pk_bf16_f32 v2, v2, v3
	ds_read_b32 v3, v47 offset:296
	ds_read_b32 v4, v47 offset:428
	s_waitcnt lgkmcnt(0)
	v_cvt_pk_bf16_f32 v3, v3, v4
	ds_read_b32 v4, v47 offset:560
	ds_read_b32 v5, v47 offset:692
	s_waitcnt lgkmcnt(0)
	v_cvt_pk_bf16_f32 v4, v4, v5
	ds_read_b32 v5, v47 offset:824
	ds_read_b32 v6, v47 offset:956
	s_waitcnt lgkmcnt(0)
	v_cvt_pk_bf16_f32 v5, v5, v6
	v_add_u32_e32 v6, s18, v40
	v_ashrrev_i32_e32 v7, 31, v6
	v_lshlrev_b64 v[6:7], 8, v[6:7]
	v_lshl_add_u64 v[6:7], v[0:1], 0, v[6:7]
	global_store_dwordx4 v[6:7], v[2:5], off
	ds_read_b32 v2, v47 offset:64
	ds_read_b32 v3, v47 offset:196
	s_waitcnt lgkmcnt(0)
	v_cvt_pk_bf16_f32 v2, v2, v3
	ds_read_b32 v3, v47 offset:328
	ds_read_b32 v4, v47 offset:460
	s_waitcnt lgkmcnt(0)
	v_cvt_pk_bf16_f32 v3, v3, v4
	ds_read_b32 v4, v47 offset:592
	ds_read_b32 v5, v47 offset:724
	s_waitcnt lgkmcnt(0)
	v_cvt_pk_bf16_f32 v4, v4, v5
	ds_read_b32 v5, v47 offset:856
	ds_read_b32 v6, v47 offset:988
	s_waitcnt lgkmcnt(0)
	v_cvt_pk_bf16_f32 v5, v5, v6
	v_add_u32_e32 v6, s18, v41
	v_ashrrev_i32_e32 v7, 31, v6
	v_lshlrev_b64 v[6:7], 8, v[6:7]
	v_lshl_add_u64 v[6:7], v[0:1], 0, v[6:7]
	global_store_dwordx4 v[6:7], v[2:5], off
	ds_read_b32 v2, v47 offset:96
	ds_read_b32 v3, v47 offset:228
	s_waitcnt lgkmcnt(0)
	v_cvt_pk_bf16_f32 v2, v2, v3
	ds_read_b32 v3, v47 offset:360
	ds_read_b32 v4, v47 offset:492
	s_waitcnt lgkmcnt(0)
	v_cvt_pk_bf16_f32 v3, v3, v4
	ds_read_b32 v4, v47 offset:624
	ds_read_b32 v5, v47 offset:756
	s_waitcnt lgkmcnt(0)
	v_cvt_pk_bf16_f32 v4, v4, v5
	ds_read_b32 v5, v47 offset:888
	ds_read_b32 v6, v47 offset:1020
	s_waitcnt lgkmcnt(0)
	v_cvt_pk_bf16_f32 v5, v5, v6
	v_add_u32_e32 v6, s18, v42
	v_ashrrev_i32_e32 v7, 31, v6
	v_lshlrev_b64 v[6:7], 8, v[6:7]
	v_lshl_add_u64 v[0:1], v[0:1], 0, v[6:7]
	global_store_dwordx4 v[0:1], v[2:5], off
	s_waitcnt lgkmcnt(0)

.LBB0_156:
	s_andn2_b64 vcc, exec, s[18:19]
	s_cbranch_vccnz .LBB0_158
	s_add_i32 s18, s44, 0xffffe980
	s_and_b32 s92, s18, 0xffffff80
	s_cmpk_lt_u32 s18, 0x80
	s_cselect_b32 s19, s36, s38
	s_cselect_b32 s20, s35, s37
	s_lshl_b32 s18, s44, 5
	s_and_b32 s18, s18, 0x60
	s_lshl_b32 s21, s18, 2
	s_add_u32 s22, s20, s21
	s_addc_u32 s23, s19, 0
	s_lshl_b32 s19, s44, 4
	s_and_b32 s19, s19, 0x7c0
	s_waitcnt lgkmcnt(0)
	v_add_u32_e32 v0, s19, v37
	v_lshlrev_b32_e32 v136, 2, v8
	v_ashrrev_i32_e32 v1, 31, v0
	v_lshl_add_u64 v[4:5], s[22:23], 0, v[136:137]
	v_lshlrev_b64 v[0:1], 9, v[0:1]
	v_lshl_add_u64 v[0:1], v[4:5], 0, v[0:1]
	global_load_dwordx4 v[0:3], v[0:1], off
	v_add_u32_e32 v236, s19, v40
	v_ashrrev_i32_e32 v237, 31, v236
	v_lshlrev_b64 v[236:237], 9, v[236:237]
	v_lshl_add_u64 v[236:237], v[4:5], 0, v[236:237]
	global_load_dwordx4 v[228:231], v[236:237], off
	v_add_u32_e32 v236, s19, v41
	v_ashrrev_i32_e32 v237, 31, v236
	v_lshlrev_b64 v[236:237], 9, v[236:237]
	v_lshl_add_u64 v[236:237], v[4:5], 0, v[236:237]
	global_load_dwordx4 v[232:235], v[236:237], off
	v_add_u32_e32 v6, v38, v39
	v_add_u32_e32 v7, 0x420, v6
	s_lshl_b64 s[20:21], s[92:93], 12
	s_add_u32 s20, s41, s20
	s_addc_u32 s21, s42, s21
	v_lshlrev_b32_e32 v136, 1, v10
	s_waitcnt vmcnt(2)
	ds_write2_b32 v6, v0, v1 offset1:1
	ds_write2_b32 v6, v2, v3 offset0:2 offset1:3
	v_add_u32_e32 v0, s19, v42
	v_ashrrev_i32_e32 v1, 31, v0
	v_lshlrev_b64 v[0:1], 9, v[0:1]
	v_lshl_add_u64 v[0:1], v[4:5], 0, v[0:1]
	global_load_dwordx4 v[0:3], v[0:1], off
	s_waitcnt vmcnt(2)
	ds_write2_b32 v7, v228, v229 offset1:1
	v_add_u32_e32 v236, 0x428, v6
	ds_write2_b32 v236, v230, v231 offset1:1
	v_add_u32_e32 v236, s19, v43
	v_ashrrev_i32_e32 v237, 31, v236
	v_lshlrev_b64 v[236:237], 9, v[236:237]
	v_lshl_add_u64 v[236:237], v[4:5], 0, v[236:237]
	global_load_dwordx4 v[228:231], v[236:237], off
	v_add_u32_e32 v7, 0x840, v6
	s_waitcnt vmcnt(2)
	ds_write2_b32 v7, v232, v233 offset1:1
	v_add_u32_e32 v236, 0x848, v6
	ds_write2_b32 v236, v234, v235 offset1:1
	v_add_u32_e32 v236, s19, v44
	v_ashrrev_i32_e32 v237, 31, v236
	v_lshlrev_b64 v[236:237], 9, v[236:237]
	v_lshl_add_u64 v[236:237], v[4:5], 0, v[236:237]
	global_load_dwordx4 v[232:235], v[236:237], off
	v_add_u32_e32 v7, 0xc60, v6
	s_waitcnt vmcnt(2)
	ds_write2_b32 v7, v0, v1 offset1:1
	v_add_u32_e32 v0, 0xc68, v6
	ds_write2_b32 v0, v2, v3 offset1:1
	v_add_u32_e32 v0, s19, v45
	v_ashrrev_i32_e32 v1, 31, v0
	v_lshlrev_b64 v[0:1], 9, v[0:1]
	v_lshl_add_u64 v[0:1], v[4:5], 0, v[0:1]
	global_load_dwordx4 v[0:3], v[0:1], off
	v_add_u32_e32 v7, 0x1080, v6
	s_waitcnt vmcnt(2)
	ds_write2_b32 v7, v228, v229 offset1:1
	v_add_u32_e32 v236, 0x1088, v6
	ds_write2_b32 v236, v230, v231 offset1:1
	v_add_u32_e32 v236, s19, v46
	v_ashrrev_i32_e32 v237, 31, v236
	v_lshlrev_b64 v[236:237], 9, v[236:237]
	v_lshl_add_u64 v[236:237], v[4:5], 0, v[236:237]
	global_load_dwordx4 v[228:231], v[236:237], off
	v_add_u32_e32 v7, 0x14a0, v6
	s_waitcnt vmcnt(2)
	ds_write2_b32 v7, v232, v233 offset1:1
	v_add_u32_e32 v236, 0x14a8, v6
	ds_write2_b32 v236, v234, v235 offset1:1
	v_add_u32_e32 v7, 0x18c0, v6
	s_waitcnt vmcnt(1)
	ds_write2_b32 v7, v0, v1 offset1:1
	v_add_u32_e32 v0, 0x18c8, v6
	ds_write2_b32 v0, v2, v3 offset1:1
	v_add_u32_e32 v4, 0x1ce0, v6
	s_lshl_b32 s19, s19, 1
	s_add_u32 s20, s20, s19
	s_addc_u32 s21, s21, 0
	s_waitcnt vmcnt(0)
	ds_write2_b32 v4, v228, v229 offset1:1
	v_add_u32_e32 v236, 0x1ce8, v6
	ds_write2_b32 v236, v230, v231 offset1:1
	s_waitcnt lgkmcnt(0)
	ds_read_b32 v2, v47
	ds_read_b32 v3, v47 offset:132
	v_lshl_add_u64 v[0:1], s[20:21], 0, v[136:137]
	s_waitcnt lgkmcnt(0)
	v_cvt_pk_bf16_f32 v2, v2, v3
	ds_read_b32 v3, v47 offset:264
	ds_read_b32 v4, v47 offset:396
	s_waitcnt lgkmcnt(0)
	v_cvt_pk_bf16_f32 v3, v3, v4
	ds_read_b32 v4, v47 offset:528
	ds_read_b32 v5, v47 offset:660
	s_waitcnt lgkmcnt(0)
	v_cvt_pk_bf16_f32 v4, v4, v5
	ds_read_b32 v5, v47 offset:792
	ds_read_b32 v6, v47 offset:924
	s_waitcnt lgkmcnt(0)
	v_cvt_pk_bf16_f32 v5, v5, v6
	v_add_u32_e32 v6, s18, v37
	v_ashrrev_i32_e32 v7, 31, v6
	v_lshlrev_b64 v[6:7], 12, v[6:7]
	v_lshl_add_u64 v[6:7], v[0:1], 0, v[6:7]
	global_store_dwordx4 v[6:7], v[2:5], off
	ds_read_b32 v2, v47 offset:32
	ds_read_b32 v3, v47 offset:164
	s_waitcnt lgkmcnt(0)
	v_cvt_pk_bf16_f32 v2, v2, v3
	ds_read_b32 v3, v47 offset:296
	ds_read_b32 v4, v47 offset:428
	s_waitcnt lgkmcnt(0)
	v_cvt_pk_bf16_f32 v3, v3, v4
	ds_read_b32 v4, v47 offset:560
	ds_read_b32 v5, v47 offset:692
	s_waitcnt lgkmcnt(0)
	v_cvt_pk_bf16_f32 v4, v4, v5
	ds_read_b32 v5, v47 offset:824
	ds_read_b32 v6, v47 offset:956
	s_waitcnt lgkmcnt(0)
	v_cvt_pk_bf16_f32 v5, v5, v6
	v_add_u32_e32 v6, s18, v40
	v_ashrrev_i32_e32 v7, 31, v6
	v_lshlrev_b64 v[6:7], 12, v[6:7]
	v_lshl_add_u64 v[6:7], v[0:1], 0, v[6:7]
	global_store_dwordx4 v[6:7], v[2:5], off
	ds_read_b32 v2, v47 offset:64
	ds_read_b32 v3, v47 offset:196
	s_waitcnt lgkmcnt(0)
	v_cvt_pk_bf16_f32 v2, v2, v3
	ds_read_b32 v3, v47 offset:328
	ds_read_b32 v4, v47 offset:460
	s_waitcnt lgkmcnt(0)
	v_cvt_pk_bf16_f32 v3, v3, v4
	ds_read_b32 v4, v47 offset:592
	ds_read_b32 v5, v47 offset:724
	s_waitcnt lgkmcnt(0)
	v_cvt_pk_bf16_f32 v4, v4, v5
	ds_read_b32 v5, v47 offset:856
	ds_read_b32 v6, v47 offset:988
	s_waitcnt lgkmcnt(0)
	v_cvt_pk_bf16_f32 v5, v5, v6
	v_add_u32_e32 v6, s18, v41
	v_ashrrev_i32_e32 v7, 31, v6
	v_lshlrev_b64 v[6:7], 12, v[6:7]
	v_lshl_add_u64 v[6:7], v[0:1], 0, v[6:7]
	global_store_dwordx4 v[6:7], v[2:5], off
	ds_read_b32 v2, v47 offset:96
	ds_read_b32 v3, v47 offset:228
	s_waitcnt lgkmcnt(0)
	v_cvt_pk_bf16_f32 v2, v2, v3
	ds_read_b32 v3, v47 offset:360
	ds_read_b32 v4, v47 offset:492
	s_waitcnt lgkmcnt(0)
	v_cvt_pk_bf16_f32 v3, v3, v4
	ds_read_b32 v4, v47 offset:624
	ds_read_b32 v5, v47 offset:756
	s_waitcnt lgkmcnt(0)
	v_cvt_pk_bf16_f32 v4, v4, v5
	ds_read_b32 v5, v47 offset:888
	ds_read_b32 v6, v47 offset:1020
	s_waitcnt lgkmcnt(0)
	v_cvt_pk_bf16_f32 v5, v5, v6
	v_add_u32_e32 v6, s18, v42
	v_ashrrev_i32_e32 v7, 31, v6
	v_lshlrev_b64 v[6:7], 12, v[6:7]
	v_lshl_add_u64 v[0:1], v[0:1], 0, v[6:7]
	global_store_dwordx4 v[0:1], v[2:5], off
	s_waitcnt lgkmcnt(0)

.LBB0_159:
	s_andn2_b64 vcc, exec, s[18:19]
	s_cbranch_vccnz .LBB0_161
	s_lshl_b32 s18, s44, 5
	s_and_b32 s20, s18, 0x3e0
	s_lshl_b32 s18, s44, 1
	s_and_b32 s18, s18, 0x3fc0
	s_addk_i32 s18, 0xd700
	s_waitcnt lgkmcnt(0)
	v_add_u32_e32 v0, s18, v37
	s_lshl_b32 s92, s20, 2
	v_ashrrev_i32_e32 v1, 31, v0
	v_lshl_add_u64 v[4:5], v[12:13], 0, s[92:93]
	v_lshlrev_b64 v[0:1], 12, v[0:1]
	v_lshl_add_u64 v[0:1], v[4:5], 0, v[0:1]
	global_load_dwordx4 v[0:3], v[0:1], off
	v_add_u32_e32 v236, s18, v40
	v_ashrrev_i32_e32 v237, 31, v236
	v_lshlrev_b64 v[236:237], 12, v[236:237]
	v_lshl_add_u64 v[236:237], v[4:5], 0, v[236:237]
	global_load_dwordx4 v[228:231], v[236:237], off
	v_add_u32_e32 v236, s18, v41
	v_ashrrev_i32_e32 v237, 31, v236
	v_lshlrev_b64 v[236:237], 12, v[236:237]
	v_lshl_add_u64 v[236:237], v[4:5], 0, v[236:237]
	global_load_dwordx4 v[232:235], v[236:237], off
	v_add_u32_e32 v6, v38, v39
	v_add_u32_e32 v7, 0x420, v6
	s_mov_b32 s19, s93
	s_waitcnt vmcnt(2)
	ds_write2_b32 v6, v0, v1 offset1:1
	ds_write2_b32 v6, v2, v3 offset0:2 offset1:3
	v_add_u32_e32 v0, s18, v42
	v_ashrrev_i32_e32 v1, 31, v0
	v_lshlrev_b64 v[0:1], 12, v[0:1]
	v_lshl_add_u64 v[0:1], v[4:5], 0, v[0:1]
	global_load_dwordx4 v[0:3], v[0:1], off
	s_waitcnt vmcnt(2)
	ds_write2_b32 v7, v228, v229 offset1:1
	v_add_u32_e32 v236, 0x428, v6
	ds_write2_b32 v236, v230, v231 offset1:1
	v_add_u32_e32 v236, s18, v43
	v_ashrrev_i32_e32 v237, 31, v236
	v_lshlrev_b64 v[236:237], 12, v[236:237]
	v_lshl_add_u64 v[236:237], v[4:5], 0, v[236:237]
	global_load_dwordx4 v[228:231], v[236:237], off
	v_add_u32_e32 v7, 0x840, v6
	s_waitcnt vmcnt(2)
	ds_write2_b32 v7, v232, v233 offset1:1
	v_add_u32_e32 v236, 0x848, v6
	ds_write2_b32 v236, v234, v235 offset1:1
	v_add_u32_e32 v236, s18, v44
	v_ashrrev_i32_e32 v237, 31, v236
	v_lshlrev_b64 v[236:237], 12, v[236:237]
	v_lshl_add_u64 v[236:237], v[4:5], 0, v[236:237]
	global_load_dwordx4 v[232:235], v[236:237], off
	v_add_u32_e32 v7, 0xc60, v6
	s_waitcnt vmcnt(2)
	ds_write2_b32 v7, v0, v1 offset1:1
	v_add_u32_e32 v0, 0xc68, v6
	ds_write2_b32 v0, v2, v3 offset1:1
	v_add_u32_e32 v0, s18, v45
	v_ashrrev_i32_e32 v1, 31, v0
	v_lshlrev_b64 v[0:1], 12, v[0:1]
	v_lshl_add_u64 v[0:1], v[4:5], 0, v[0:1]
	global_load_dwordx4 v[0:3], v[0:1], off
	v_add_u32_e32 v7, 0x1080, v6
	s_waitcnt vmcnt(2)
	ds_write2_b32 v7, v228, v229 offset1:1
	v_add_u32_e32 v236, 0x1088, v6
	ds_write2_b32 v236, v230, v231 offset1:1
	v_add_u32_e32 v236, s18, v46
	v_ashrrev_i32_e32 v237, 31, v236
	v_lshlrev_b64 v[236:237], 12, v[236:237]
	v_lshl_add_u64 v[236:237], v[4:5], 0, v[236:237]
	global_load_dwordx4 v[228:231], v[236:237], off
	v_add_u32_e32 v7, 0x14a0, v6
	s_waitcnt vmcnt(2)
	ds_write2_b32 v7, v232, v233 offset1:1
	v_add_u32_e32 v236, 0x14a8, v6
	ds_write2_b32 v236, v234, v235 offset1:1
	v_add_u32_e32 v7, 0x18c0, v6
	s_waitcnt vmcnt(1)
	ds_write2_b32 v7, v0, v1 offset1:1
	v_add_u32_e32 v0, 0x18c8, v6
	ds_write2_b32 v0, v2, v3 offset1:1
	v_add_u32_e32 v4, 0x1ce0, v6
	s_waitcnt vmcnt(0)
	ds_write2_b32 v4, v228, v229 offset1:1
	v_add_u32_e32 v236, 0x1ce8, v6
	ds_write2_b32 v236, v230, v231 offset1:1
	s_waitcnt lgkmcnt(0)
	ds_read_b32 v2, v47
	ds_read_b32 v3, v47 offset:132
	v_lshl_add_u64 v[0:1], s[18:19], 1, v[14:15]
	s_waitcnt lgkmcnt(0)
	v_cvt_pk_bf16_f32 v2, v2, v3
	ds_read_b32 v3, v47 offset:264
	ds_read_b32 v4, v47 offset:396
	s_waitcnt lgkmcnt(0)
	v_cvt_pk_bf16_f32 v3, v3, v4
	ds_read_b32 v4, v47 offset:528
	ds_read_b32 v5, v47 offset:660
	s_waitcnt lgkmcnt(0)
	v_cvt_pk_bf16_f32 v4, v4, v5
	ds_read_b32 v5, v47 offset:792
	ds_read_b32 v6, v47 offset:924
	s_waitcnt lgkmcnt(0)
	v_cvt_pk_bf16_f32 v5, v5, v6
	v_add_u32_e32 v6, s20, v37
	v_ashrrev_i32_e32 v7, 31, v6
	v_lshlrev_b64 v[6:7], 11, v[6:7]
	v_lshl_add_u64 v[6:7], v[0:1], 0, v[6:7]
	global_store_dwordx4 v[6:7], v[2:5], off
	ds_read_b32 v2, v47 offset:32
	ds_read_b32 v3, v47 offset:164
	s_waitcnt lgkmcnt(0)
	v_cvt_pk_bf16_f32 v2, v2, v3
	ds_read_b32 v3, v47 offset:296
	ds_read_b32 v4, v47 offset:428
	s_waitcnt lgkmcnt(0)
	v_cvt_pk_bf16_f32 v3, v3, v4
	ds_read_b32 v4, v47 offset:560
	ds_read_b32 v5, v47 offset:692
	s_waitcnt lgkmcnt(0)
	v_cvt_pk_bf16_f32 v4, v4, v5
	ds_read_b32 v5, v47 offset:824
	ds_read_b32 v6, v47 offset:956
	s_waitcnt lgkmcnt(0)
	v_cvt_pk_bf16_f32 v5, v5, v6
	v_add_u32_e32 v6, s20, v40
	v_ashrrev_i32_e32 v7, 31, v6
	v_lshlrev_b64 v[6:7], 11, v[6:7]
	v_lshl_add_u64 v[6:7], v[0:1], 0, v[6:7]
	global_store_dwordx4 v[6:7], v[2:5], off
	ds_read_b32 v2, v47 offset:64
	ds_read_b32 v3, v47 offset:196
	s_waitcnt lgkmcnt(0)
	v_cvt_pk_bf16_f32 v2, v2, v3
	ds_read_b32 v3, v47 offset:328
	ds_read_b32 v4, v47 offset:460
	s_waitcnt lgkmcnt(0)
	v_cvt_pk_bf16_f32 v3, v3, v4
	ds_read_b32 v4, v47 offset:592
	ds_read_b32 v5, v47 offset:724
	s_waitcnt lgkmcnt(0)
	v_cvt_pk_bf16_f32 v4, v4, v5
	ds_read_b32 v5, v47 offset:856
	ds_read_b32 v6, v47 offset:988
	s_waitcnt lgkmcnt(0)
	v_cvt_pk_bf16_f32 v5, v5, v6
	v_add_u32_e32 v6, s20, v41
	v_ashrrev_i32_e32 v7, 31, v6
	v_lshlrev_b64 v[6:7], 11, v[6:7]
	v_lshl_add_u64 v[6:7], v[0:1], 0, v[6:7]
	global_store_dwordx4 v[6:7], v[2:5], off
	ds_read_b32 v2, v47 offset:96
	ds_read_b32 v3, v47 offset:228
	s_waitcnt lgkmcnt(0)
	v_cvt_pk_bf16_f32 v2, v2, v3
	ds_read_b32 v3, v47 offset:360
	ds_read_b32 v4, v47 offset:492
	s_waitcnt lgkmcnt(0)
	v_cvt_pk_bf16_f32 v3, v3, v4
	ds_read_b32 v4, v47 offset:624
	ds_read_b32 v5, v47 offset:756
	s_waitcnt lgkmcnt(0)
	v_cvt_pk_bf16_f32 v4, v4, v5
	ds_read_b32 v5, v47 offset:888
	ds_read_b32 v6, v47 offset:1020
	s_waitcnt lgkmcnt(0)
	v_cvt_pk_bf16_f32 v5, v5, v6
	v_add_u32_e32 v6, s20, v42
	v_ashrrev_i32_e32 v7, 31, v6
	v_lshlrev_b64 v[6:7], 11, v[6:7]
	v_lshl_add_u64 v[0:1], v[0:1], 0, v[6:7]
	global_store_dwordx4 v[0:1], v[2:5], off
	s_waitcnt lgkmcnt(0)

.LBB0_162:
	s_andn2_b64 vcc, exec, s[18:19]
	s_cbranch_vccnz .LBB0_164
	s_lshl_b32 s18, s44, 5
	s_and_b32 s20, s18, 0x3e0
	s_lshl_b32 s18, s44, 1
	s_and_b32 s18, s18, 0x3fc0
	s_addk_i32 s18, 0xd880
	s_waitcnt lgkmcnt(0)
	v_add_u32_e32 v0, s18, v37
	s_lshl_b32 s92, s20, 2
	v_ashrrev_i32_e32 v1, 31, v0
	v_lshl_add_u64 v[4:5], v[18:19], 0, s[92:93]
	v_lshlrev_b64 v[0:1], 12, v[0:1]
	v_lshl_add_u64 v[0:1], v[4:5], 0, v[0:1]
	global_load_dwordx4 v[0:3], v[0:1], off
	v_add_u32_e32 v236, s18, v40
	v_ashrrev_i32_e32 v237, 31, v236
	v_lshlrev_b64 v[236:237], 12, v[236:237]
	v_lshl_add_u64 v[236:237], v[4:5], 0, v[236:237]
	global_load_dwordx4 v[228:231], v[236:237], off
	v_add_u32_e32 v236, s18, v41
	v_ashrrev_i32_e32 v237, 31, v236
	v_lshlrev_b64 v[236:237], 12, v[236:237]
	v_lshl_add_u64 v[236:237], v[4:5], 0, v[236:237]
	global_load_dwordx4 v[232:235], v[236:237], off
	v_add_u32_e32 v6, v38, v39
	v_add_u32_e32 v7, 0x420, v6
	s_mov_b32 s19, s93
	s_waitcnt vmcnt(2)
	ds_write2_b32 v6, v0, v1 offset1:1
	ds_write2_b32 v6, v2, v3 offset0:2 offset1:3
	v_add_u32_e32 v0, s18, v42
	v_ashrrev_i32_e32 v1, 31, v0
	v_lshlrev_b64 v[0:1], 12, v[0:1]
	v_lshl_add_u64 v[0:1], v[4:5], 0, v[0:1]
	global_load_dwordx4 v[0:3], v[0:1], off
	s_waitcnt vmcnt(2)
	ds_write2_b32 v7, v228, v229 offset1:1
	v_add_u32_e32 v236, 0x428, v6
	ds_write2_b32 v236, v230, v231 offset1:1
	v_add_u32_e32 v236, s18, v43
	v_ashrrev_i32_e32 v237, 31, v236
	v_lshlrev_b64 v[236:237], 12, v[236:237]
	v_lshl_add_u64 v[236:237], v[4:5], 0, v[236:237]
	global_load_dwordx4 v[228:231], v[236:237], off
	v_add_u32_e32 v7, 0x840, v6
	s_waitcnt vmcnt(2)
	ds_write2_b32 v7, v232, v233 offset1:1
	v_add_u32_e32 v236, 0x848, v6
	ds_write2_b32 v236, v234, v235 offset1:1
	v_add_u32_e32 v236, s18, v44
	v_ashrrev_i32_e32 v237, 31, v236
	v_lshlrev_b64 v[236:237], 12, v[236:237]
	v_lshl_add_u64 v[236:237], v[4:5], 0, v[236:237]
	global_load_dwordx4 v[232:235], v[236:237], off
	v_add_u32_e32 v7, 0xc60, v6
	s_waitcnt vmcnt(2)
	ds_write2_b32 v7, v0, v1 offset1:1
	v_add_u32_e32 v0, 0xc68, v6
	ds_write2_b32 v0, v2, v3 offset1:1
	v_add_u32_e32 v0, s18, v45
	v_ashrrev_i32_e32 v1, 31, v0
	v_lshlrev_b64 v[0:1], 12, v[0:1]
	v_lshl_add_u64 v[0:1], v[4:5], 0, v[0:1]
	global_load_dwordx4 v[0:3], v[0:1], off
	v_add_u32_e32 v7, 0x1080, v6
	s_waitcnt vmcnt(2)
	ds_write2_b32 v7, v228, v229 offset1:1
	v_add_u32_e32 v236, 0x1088, v6
	ds_write2_b32 v236, v230, v231 offset1:1
	v_add_u32_e32 v236, s18, v46
	v_ashrrev_i32_e32 v237, 31, v236
	v_lshlrev_b64 v[236:237], 12, v[236:237]
	v_lshl_add_u64 v[236:237], v[4:5], 0, v[236:237]
	global_load_dwordx4 v[228:231], v[236:237], off
	v_add_u32_e32 v7, 0x14a0, v6
	s_waitcnt vmcnt(2)
	ds_write2_b32 v7, v232, v233 offset1:1
	v_add_u32_e32 v236, 0x14a8, v6
	ds_write2_b32 v236, v234, v235 offset1:1
	v_add_u32_e32 v7, 0x18c0, v6
	s_waitcnt vmcnt(1)
	ds_write2_b32 v7, v0, v1 offset1:1
	v_add_u32_e32 v0, 0x18c8, v6
	ds_write2_b32 v0, v2, v3 offset1:1
	v_add_u32_e32 v4, 0x1ce0, v6
	s_waitcnt vmcnt(0)
	ds_write2_b32 v4, v228, v229 offset1:1
	v_add_u32_e32 v236, 0x1ce8, v6
	ds_write2_b32 v236, v230, v231 offset1:1
	s_waitcnt lgkmcnt(0)
	ds_read_b32 v2, v47
	ds_read_b32 v3, v47 offset:132
	v_lshl_add_u64 v[0:1], s[18:19], 1, v[20:21]
	s_waitcnt lgkmcnt(0)
	v_cvt_pk_bf16_f32 v2, v2, v3
	ds_read_b32 v3, v47 offset:264
	ds_read_b32 v4, v47 offset:396
	s_waitcnt lgkmcnt(0)
	v_cvt_pk_bf16_f32 v3, v3, v4
	ds_read_b32 v4, v47 offset:528
	ds_read_b32 v5, v47 offset:660
	s_waitcnt lgkmcnt(0)
	v_cvt_pk_bf16_f32 v4, v4, v5
	ds_read_b32 v5, v47 offset:792
	ds_read_b32 v6, v47 offset:924
	s_waitcnt lgkmcnt(0)
	v_cvt_pk_bf16_f32 v5, v5, v6
	v_add_u32_e32 v6, s20, v37
	v_mad_i64_i32 v[6:7], s[18:19], v6, s6, v[0:1]
	global_store_dwordx4 v[6:7], v[2:5], off
	ds_read_b32 v2, v47 offset:32
	ds_read_b32 v3, v47 offset:164
	s_waitcnt lgkmcnt(0)
	v_cvt_pk_bf16_f32 v2, v2, v3
	ds_read_b32 v3, v47 offset:296
	ds_read_b32 v4, v47 offset:428
	s_waitcnt lgkmcnt(0)
	v_cvt_pk_bf16_f32 v3, v3, v4
	ds_read_b32 v4, v47 offset:560
	ds_read_b32 v5, v47 offset:692
	s_waitcnt lgkmcnt(0)
	v_cvt_pk_bf16_f32 v4, v4, v5
	ds_read_b32 v5, v47 offset:824
	ds_read_b32 v6, v47 offset:956
	s_waitcnt lgkmcnt(0)
	v_cvt_pk_bf16_f32 v5, v5, v6
	v_add_u32_e32 v6, s20, v40
	v_mad_i64_i32 v[6:7], s[18:19], v6, s6, v[0:1]
	global_store_dwordx4 v[6:7], v[2:5], off
	ds_read_b32 v2, v47 offset:64
	ds_read_b32 v3, v47 offset:196
	s_waitcnt lgkmcnt(0)
	v_cvt_pk_bf16_f32 v2, v2, v3
	ds_read_b32 v3, v47 offset:328
	ds_read_b32 v4, v47 offset:460
	s_waitcnt lgkmcnt(0)
	v_cvt_pk_bf16_f32 v3, v3, v4
	ds_read_b32 v4, v47 offset:592
	ds_read_b32 v5, v47 offset:724
	s_waitcnt lgkmcnt(0)
	v_cvt_pk_bf16_f32 v4, v4, v5
	ds_read_b32 v5, v47 offset:856
	ds_read_b32 v6, v47 offset:988
	s_waitcnt lgkmcnt(0)
	v_cvt_pk_bf16_f32 v5, v5, v6
	v_add_u32_e32 v6, s20, v41
	v_mad_i64_i32 v[6:7], s[18:19], v6, s6, v[0:1]
	global_store_dwordx4 v[6:7], v[2:5], off
	ds_read_b32 v2, v47 offset:96
	ds_read_b32 v3, v47 offset:228
	s_waitcnt lgkmcnt(0)
	v_cvt_pk_bf16_f32 v2, v2, v3
	ds_read_b32 v3, v47 offset:360
	ds_read_b32 v4, v47 offset:492
	s_waitcnt lgkmcnt(0)
	v_cvt_pk_bf16_f32 v3, v3, v4
	ds_read_b32 v4, v47 offset:624
	ds_read_b32 v5, v47 offset:756
	s_waitcnt lgkmcnt(0)
	v_cvt_pk_bf16_f32 v4, v4, v5
	ds_read_b32 v5, v47 offset:888
	ds_read_b32 v6, v47 offset:1020
	s_waitcnt lgkmcnt(0)
	v_cvt_pk_bf16_f32 v5, v5, v6
	v_add_u32_e32 v6, s20, v42
	v_mad_i64_i32 v[0:1], s[18:19], v6, s6, v[0:1]
	global_store_dwordx4 v[0:1], v[2:5], off
	s_waitcnt lgkmcnt(0)

.LBB0_165:
	s_andn2_b64 vcc, exec, s[18:19]
	s_cbranch_vccnz .LBB0_167
	s_lshl_b32 s18, s44, 5
	s_and_b32 s20, s18, 0x3e0
	s_lshl_b32 s18, s44, 1
	s_and_b32 s18, s18, 0x3fc0
	s_addk_i32 s18, 0xda80
	s_waitcnt lgkmcnt(0)
	v_add_u32_e32 v0, s18, v37
	s_lshl_b32 s92, s20, 2
	v_ashrrev_i32_e32 v1, 31, v0
	v_lshl_add_u64 v[4:5], v[22:23], 0, s[92:93]
	v_lshlrev_b64 v[0:1], 12, v[0:1]
	v_lshl_add_u64 v[0:1], v[4:5], 0, v[0:1]
	global_load_dwordx4 v[0:3], v[0:1], off
	v_add_u32_e32 v236, s18, v40
	v_ashrrev_i32_e32 v237, 31, v236
	v_lshlrev_b64 v[236:237], 12, v[236:237]
	v_lshl_add_u64 v[236:237], v[4:5], 0, v[236:237]
	global_load_dwordx4 v[228:231], v[236:237], off
	v_add_u32_e32 v236, s18, v41
	v_ashrrev_i32_e32 v237, 31, v236
	v_lshlrev_b64 v[236:237], 12, v[236:237]
	v_lshl_add_u64 v[236:237], v[4:5], 0, v[236:237]
	global_load_dwordx4 v[232:235], v[236:237], off
	v_add_u32_e32 v6, v38, v39
	v_add_u32_e32 v7, 0x420, v6
	s_mov_b32 s19, s93
	s_waitcnt vmcnt(2)
	ds_write2_b32 v6, v0, v1 offset1:1
	ds_write2_b32 v6, v2, v3 offset0:2 offset1:3
	v_add_u32_e32 v0, s18, v42
	v_ashrrev_i32_e32 v1, 31, v0
	v_lshlrev_b64 v[0:1], 12, v[0:1]
	v_lshl_add_u64 v[0:1], v[4:5], 0, v[0:1]
	global_load_dwordx4 v[0:3], v[0:1], off
	s_waitcnt vmcnt(2)
	ds_write2_b32 v7, v228, v229 offset1:1
	v_add_u32_e32 v236, 0x428, v6
	ds_write2_b32 v236, v230, v231 offset1:1
	v_add_u32_e32 v236, s18, v43
	v_ashrrev_i32_e32 v237, 31, v236
	v_lshlrev_b64 v[236:237], 12, v[236:237]
	v_lshl_add_u64 v[236:237], v[4:5], 0, v[236:237]
	global_load_dwordx4 v[228:231], v[236:237], off
	v_add_u32_e32 v7, 0x840, v6
	s_waitcnt vmcnt(2)
	ds_write2_b32 v7, v232, v233 offset1:1
	v_add_u32_e32 v236, 0x848, v6
	ds_write2_b32 v236, v234, v235 offset1:1
	v_add_u32_e32 v236, s18, v44
	v_ashrrev_i32_e32 v237, 31, v236
	v_lshlrev_b64 v[236:237], 12, v[236:237]
	v_lshl_add_u64 v[236:237], v[4:5], 0, v[236:237]
	global_load_dwordx4 v[232:235], v[236:237], off
	v_add_u32_e32 v7, 0xc60, v6
	s_waitcnt vmcnt(2)
	ds_write2_b32 v7, v0, v1 offset1:1
	v_add_u32_e32 v0, 0xc68, v6
	ds_write2_b32 v0, v2, v3 offset1:1
	v_add_u32_e32 v0, s18, v45
	v_ashrrev_i32_e32 v1, 31, v0
	v_lshlrev_b64 v[0:1], 12, v[0:1]
	v_lshl_add_u64 v[0:1], v[4:5], 0, v[0:1]
	global_load_dwordx4 v[0:3], v[0:1], off
	v_add_u32_e32 v7, 0x1080, v6
	s_waitcnt vmcnt(2)
	ds_write2_b32 v7, v228, v229 offset1:1
	v_add_u32_e32 v236, 0x1088, v6
	ds_write2_b32 v236, v230, v231 offset1:1
	v_add_u32_e32 v236, s18, v46
	v_ashrrev_i32_e32 v237, 31, v236
	v_lshlrev_b64 v[236:237], 12, v[236:237]
	v_lshl_add_u64 v[236:237], v[4:5], 0, v[236:237]
	global_load_dwordx4 v[228:231], v[236:237], off
	v_add_u32_e32 v7, 0x14a0, v6
	s_waitcnt vmcnt(2)
	ds_write2_b32 v7, v232, v233 offset1:1
	v_add_u32_e32 v236, 0x14a8, v6
	ds_write2_b32 v236, v234, v235 offset1:1
	v_add_u32_e32 v7, 0x18c0, v6
	s_waitcnt vmcnt(1)
	ds_write2_b32 v7, v0, v1 offset1:1
	v_add_u32_e32 v0, 0x18c8, v6
	ds_write2_b32 v0, v2, v3 offset1:1
	v_add_u32_e32 v4, 0x1ce0, v6
	s_waitcnt vmcnt(0)
	ds_write2_b32 v4, v228, v229 offset1:1
	v_add_u32_e32 v236, 0x1ce8, v6
	ds_write2_b32 v236, v230, v231 offset1:1
	s_waitcnt lgkmcnt(0)
	ds_read_b32 v2, v47
	ds_read_b32 v3, v47 offset:132
	v_lshl_add_u64 v[0:1], s[18:19], 1, v[24:25]
	s_waitcnt lgkmcnt(0)
	v_cvt_pk_bf16_f32 v2, v2, v3
	ds_read_b32 v3, v47 offset:264
	ds_read_b32 v4, v47 offset:396
	s_waitcnt lgkmcnt(0)
	v_cvt_pk_bf16_f32 v3, v3, v4
	ds_read_b32 v4, v47 offset:528
	ds_read_b32 v5, v47 offset:660
	s_waitcnt lgkmcnt(0)
	v_cvt_pk_bf16_f32 v4, v4, v5
	ds_read_b32 v5, v47 offset:792
	ds_read_b32 v6, v47 offset:924
	s_waitcnt lgkmcnt(0)
	v_cvt_pk_bf16_f32 v5, v5, v6
	v_add_u32_e32 v6, s20, v37
	v_ashrrev_i32_e32 v7, 31, v6
	v_lshlrev_b64 v[6:7], 10, v[6:7]
	v_lshl_add_u64 v[6:7], v[0:1], 0, v[6:7]
	global_store_dwordx4 v[6:7], v[2:5], off
	ds_read_b32 v2, v47 offset:32
	ds_read_b32 v3, v47 offset:164
	s_waitcnt lgkmcnt(0)
	v_cvt_pk_bf16_f32 v2, v2, v3
	ds_read_b32 v3, v47 offset:296
	ds_read_b32 v4, v47 offset:428
	s_waitcnt lgkmcnt(0)
	v_cvt_pk_bf16_f32 v3, v3, v4
	ds_read_b32 v4, v47 offset:560
	ds_read_b32 v5, v47 offset:692
	s_waitcnt lgkmcnt(0)
	v_cvt_pk_bf16_f32 v4, v4, v5
	ds_read_b32 v5, v47 offset:824
	ds_read_b32 v6, v47 offset:956
	s_waitcnt lgkmcnt(0)
	v_cvt_pk_bf16_f32 v5, v5, v6
	v_add_u32_e32 v6, s20, v40
	v_ashrrev_i32_e32 v7, 31, v6
	v_lshlrev_b64 v[6:7], 10, v[6:7]
	v_lshl_add_u64 v[6:7], v[0:1], 0, v[6:7]
	global_store_dwordx4 v[6:7], v[2:5], off
	ds_read_b32 v2, v47 offset:64
	ds_read_b32 v3, v47 offset:196
	s_waitcnt lgkmcnt(0)
	v_cvt_pk_bf16_f32 v2, v2, v3
	ds_read_b32 v3, v47 offset:328
	ds_read_b32 v4, v47 offset:460
	s_waitcnt lgkmcnt(0)
	v_cvt_pk_bf16_f32 v3, v3, v4
	ds_read_b32 v4, v47 offset:592
	ds_read_b32 v5, v47 offset:724
	s_waitcnt lgkmcnt(0)
	v_cvt_pk_bf16_f32 v4, v4, v5
	ds_read_b32 v5, v47 offset:856
	ds_read_b32 v6, v47 offset:988
	s_waitcnt lgkmcnt(0)
	v_cvt_pk_bf16_f32 v5, v5, v6
	v_add_u32_e32 v6, s20, v41
	v_ashrrev_i32_e32 v7, 31, v6
	v_lshlrev_b64 v[6:7], 10, v[6:7]
	v_lshl_add_u64 v[6:7], v[0:1], 0, v[6:7]
	global_store_dwordx4 v[6:7], v[2:5], off
	ds_read_b32 v2, v47 offset:96
	ds_read_b32 v3, v47 offset:228
	s_waitcnt lgkmcnt(0)
	v_cvt_pk_bf16_f32 v2, v2, v3
	ds_read_b32 v3, v47 offset:360
	ds_read_b32 v4, v47 offset:492
	s_waitcnt lgkmcnt(0)
	v_cvt_pk_bf16_f32 v3, v3, v4
	ds_read_b32 v4, v47 offset:624
	ds_read_b32 v5, v47 offset:756
	s_waitcnt lgkmcnt(0)
	v_cvt_pk_bf16_f32 v4, v4, v5
	ds_read_b32 v5, v47 offset:888
	ds_read_b32 v6, v47 offset:1020
	s_waitcnt lgkmcnt(0)
	v_cvt_pk_bf16_f32 v5, v5, v6
	v_add_u32_e32 v6, s20, v42
	v_ashrrev_i32_e32 v7, 31, v6
	v_lshlrev_b64 v[6:7], 10, v[6:7]
	v_lshl_add_u64 v[0:1], v[0:1], 0, v[6:7]
	global_store_dwordx4 v[0:1], v[2:5], off
	s_waitcnt lgkmcnt(0)

.LBB0_168:
	s_andn2_b64 vcc, exec, s[18:19]
	s_cbranch_vccnz .LBB0_170
	s_lshl_b32 s18, s44, 5
	s_and_b32 s20, s18, 0x3e0
	s_lshl_b32 s18, s44, 1
	s_and_b32 s18, s18, 0x3fc0
	s_addk_i32 s18, 0xdc00
	s_waitcnt lgkmcnt(0)
	v_add_u32_e32 v0, s18, v37
	s_lshl_b32 s92, s20, 2
	v_ashrrev_i32_e32 v1, 31, v0
	v_lshl_add_u64 v[4:5], v[16:17], 0, s[92:93]
	v_lshlrev_b64 v[0:1], 12, v[0:1]
	v_lshl_add_u64 v[0:1], v[4:5], 0, v[0:1]
	global_load_dwordx4 v[0:3], v[0:1], off
	v_add_u32_e32 v236, s18, v40
	v_ashrrev_i32_e32 v237, 31, v236
	v_lshlrev_b64 v[236:237], 12, v[236:237]
	v_lshl_add_u64 v[236:237], v[4:5], 0, v[236:237]
	global_load_dwordx4 v[228:231], v[236:237], off
	v_add_u32_e32 v236, s18, v41
	v_ashrrev_i32_e32 v237, 31, v236
	v_lshlrev_b64 v[236:237], 12, v[236:237]
	v_lshl_add_u64 v[236:237], v[4:5], 0, v[236:237]
	global_load_dwordx4 v[232:235], v[236:237], off
	v_add_u32_e32 v6, v38, v39
	v_add_u32_e32 v7, 0x420, v6
	s_mov_b32 s19, s93
	s_waitcnt vmcnt(2)
	ds_write2_b32 v6, v0, v1 offset1:1
	ds_write2_b32 v6, v2, v3 offset0:2 offset1:3
	v_add_u32_e32 v0, s18, v42
	v_ashrrev_i32_e32 v1, 31, v0
	v_lshlrev_b64 v[0:1], 12, v[0:1]
	v_lshl_add_u64 v[0:1], v[4:5], 0, v[0:1]
	global_load_dwordx4 v[0:3], v[0:1], off
	s_waitcnt vmcnt(2)
	ds_write2_b32 v7, v228, v229 offset1:1
	v_add_u32_e32 v236, 0x428, v6
	ds_write2_b32 v236, v230, v231 offset1:1
	v_add_u32_e32 v236, s18, v43
	v_ashrrev_i32_e32 v237, 31, v236
	v_lshlrev_b64 v[236:237], 12, v[236:237]
	v_lshl_add_u64 v[236:237], v[4:5], 0, v[236:237]
	global_load_dwordx4 v[228:231], v[236:237], off
	v_add_u32_e32 v7, 0x840, v6
	s_waitcnt vmcnt(2)
	ds_write2_b32 v7, v232, v233 offset1:1
	v_add_u32_e32 v236, 0x848, v6
	ds_write2_b32 v236, v234, v235 offset1:1
	v_add_u32_e32 v236, s18, v44
	v_ashrrev_i32_e32 v237, 31, v236
	v_lshlrev_b64 v[236:237], 12, v[236:237]
	v_lshl_add_u64 v[236:237], v[4:5], 0, v[236:237]
	global_load_dwordx4 v[232:235], v[236:237], off
	v_add_u32_e32 v7, 0xc60, v6
	s_waitcnt vmcnt(2)
	ds_write2_b32 v7, v0, v1 offset1:1
	v_add_u32_e32 v0, 0xc68, v6
	ds_write2_b32 v0, v2, v3 offset1:1
	v_add_u32_e32 v0, s18, v45
	v_ashrrev_i32_e32 v1, 31, v0
	v_lshlrev_b64 v[0:1], 12, v[0:1]
	v_lshl_add_u64 v[0:1], v[4:5], 0, v[0:1]
	global_load_dwordx4 v[0:3], v[0:1], off
	v_add_u32_e32 v7, 0x1080, v6
	s_waitcnt vmcnt(2)
	ds_write2_b32 v7, v228, v229 offset1:1
	v_add_u32_e32 v236, 0x1088, v6
	ds_write2_b32 v236, v230, v231 offset1:1
	v_add_u32_e32 v236, s18, v46
	v_ashrrev_i32_e32 v237, 31, v236
	v_lshlrev_b64 v[236:237], 12, v[236:237]
	v_lshl_add_u64 v[236:237], v[4:5], 0, v[236:237]
	global_load_dwordx4 v[228:231], v[236:237], off
	v_add_u32_e32 v7, 0x14a0, v6
	s_waitcnt vmcnt(2)
	ds_write2_b32 v7, v232, v233 offset1:1
	v_add_u32_e32 v236, 0x14a8, v6
	ds_write2_b32 v236, v234, v235 offset1:1
	v_add_u32_e32 v7, 0x18c0, v6
	s_waitcnt vmcnt(1)
	ds_write2_b32 v7, v0, v1 offset1:1
	v_add_u32_e32 v0, 0x18c8, v6
	ds_write2_b32 v0, v2, v3 offset1:1
	v_add_u32_e32 v4, 0x1ce0, v6
	s_waitcnt vmcnt(0)
	ds_write2_b32 v4, v228, v229 offset1:1
	v_add_u32_e32 v236, 0x1ce8, v6
	ds_write2_b32 v236, v230, v231 offset1:1
	s_waitcnt lgkmcnt(0)
	ds_read_b32 v2, v47
	ds_read_b32 v3, v47 offset:132
	v_lshl_add_u64 v[0:1], s[18:19], 1, v[26:27]
	s_waitcnt lgkmcnt(0)
	v_cvt_pk_bf16_f32 v2, v2, v3
	ds_read_b32 v3, v47 offset:264
	ds_read_b32 v4, v47 offset:396
	s_waitcnt lgkmcnt(0)
	v_cvt_pk_bf16_f32 v3, v3, v4
	ds_read_b32 v4, v47 offset:528
	ds_read_b32 v5, v47 offset:660
	s_waitcnt lgkmcnt(0)
	v_cvt_pk_bf16_f32 v4, v4, v5
	ds_read_b32 v5, v47 offset:792
	ds_read_b32 v6, v47 offset:924
	s_waitcnt lgkmcnt(0)
	v_cvt_pk_bf16_f32 v5, v5, v6
	v_add_u32_e32 v6, s20, v37
	v_mad_i64_i32 v[6:7], s[18:19], v6, s6, v[0:1]
	global_store_dwordx4 v[6:7], v[2:5], off
	ds_read_b32 v2, v47 offset:32
	ds_read_b32 v3, v47 offset:164
	s_waitcnt lgkmcnt(0)
	v_cvt_pk_bf16_f32 v2, v2, v3
	ds_read_b32 v3, v47 offset:296
	ds_read_b32 v4, v47 offset:428
	s_waitcnt lgkmcnt(0)
	v_cvt_pk_bf16_f32 v3, v3, v4
	ds_read_b32 v4, v47 offset:560
	ds_read_b32 v5, v47 offset:692
	s_waitcnt lgkmcnt(0)
	v_cvt_pk_bf16_f32 v4, v4, v5
	ds_read_b32 v5, v47 offset:824
	ds_read_b32 v6, v47 offset:956
	s_waitcnt lgkmcnt(0)
	v_cvt_pk_bf16_f32 v5, v5, v6
	v_add_u32_e32 v6, s20, v40
	v_mad_i64_i32 v[6:7], s[18:19], v6, s6, v[0:1]
	global_store_dwordx4 v[6:7], v[2:5], off
	ds_read_b32 v2, v47 offset:64
	ds_read_b32 v3, v47 offset:196
	s_waitcnt lgkmcnt(0)
	v_cvt_pk_bf16_f32 v2, v2, v3
	ds_read_b32 v3, v47 offset:328
	ds_read_b32 v4, v47 offset:460
	s_waitcnt lgkmcnt(0)
	v_cvt_pk_bf16_f32 v3, v3, v4
	ds_read_b32 v4, v47 offset:592
	ds_read_b32 v5, v47 offset:724
	s_waitcnt lgkmcnt(0)
	v_cvt_pk_bf16_f32 v4, v4, v5
	ds_read_b32 v5, v47 offset:856
	ds_read_b32 v6, v47 offset:988
	s_waitcnt lgkmcnt(0)
	v_cvt_pk_bf16_f32 v5, v5, v6
	v_add_u32_e32 v6, s20, v41
	v_mad_i64_i32 v[6:7], s[18:19], v6, s6, v[0:1]
	global_store_dwordx4 v[6:7], v[2:5], off
	ds_read_b32 v2, v47 offset:96
	ds_read_b32 v3, v47 offset:228
	s_waitcnt lgkmcnt(0)
	v_cvt_pk_bf16_f32 v2, v2, v3
	ds_read_b32 v3, v47 offset:360
	ds_read_b32 v4, v47 offset:492
	s_waitcnt lgkmcnt(0)
	v_cvt_pk_bf16_f32 v3, v3, v4
	ds_read_b32 v4, v47 offset:624
	ds_read_b32 v5, v47 offset:756
	s_waitcnt lgkmcnt(0)
	v_cvt_pk_bf16_f32 v4, v4, v5
	ds_read_b32 v5, v47 offset:888
	ds_read_b32 v6, v47 offset:1020
	s_waitcnt lgkmcnt(0)
	v_cvt_pk_bf16_f32 v5, v5, v6
	v_add_u32_e32 v6, s20, v42
	v_mad_i64_i32 v[0:1], s[18:19], v6, s6, v[0:1]
	global_store_dwordx4 v[0:1], v[2:5], off
	s_waitcnt lgkmcnt(0)
